# hg_sample: the four per-token gate/input load pairs issued together (one drain instead of four)
# baseline (speedup 1.0000x reference)
.LBB0_701:
	s_andn2_b64 vcc, exec, s[4:5]
	s_cbranch_vccnz .LBB0_647
	v_mov_b32_e32 v14, v156
	s_load_dwordx2 s[4:5], s[28:29], 0x40
	s_mov_b64 s[6:7], 0xf000000
	v_ashrrev_i32_e32 v15, 8, v14
	v_add_u32_e32 v0, s66, v15
	v_add_u32_e32 v8, 0x200, v0
	v_lshlrev_b32_e32 v0, 7, v8
	v_and_b32_e32 v21, 0x7f, v14
	v_and_b32_e32 v0, 0x180, v0
	v_or_b32_e32 v1, v0, v21
	v_lshlrev_b32_e32 v12, 2, v1
	s_waitcnt lgkmcnt(0)
	global_load_dword v2, v12, s[4:5] offset:2048
	global_load_dword v3, v12, s[4:5]
	v_lshlrev_b32_e32 v64, 1, v0
	v_lshl_add_u64 v[0:1], s[30:31], 0, v[64:65]
	v_lshlrev_b32_e32 v64, 1, v21
	v_and_b32_e32 v5, -4, v8
	v_lshl_add_u64 v[0:1], v[0:1], 0, v[64:65]
	v_mad_i64_i32 v[10:11], s[8:9], v5, s71, v[0:1]
	v_lshlrev_b32_e32 v20, 9, v15
	v_bfe_u32 v17, v14, 7, 1
	v_or_b32_e32 v4, v20, v21
	v_cmp_eq_u32_e64 s[4:5], 0, v17
	v_lshl_add_u64 v[0:1], v[10:11], 0, s[6:7]
	v_lshl_add_u32 v19, v4, 2, 0
	s_waitcnt vmcnt(0)
	v_sub_f32_e32 v2, v2, v3
	v_mul_f32_e32 v2, 0x3fb8aa3b, v2
	v_exp_f32_e32 v2, v2
	s_nop 0
	v_add_f32_e32 v2, 1.0, v2
	v_div_scale_f32 v3, s[8:9], v2, v2, 1.0
	v_rcp_f32_e32 v5, v3
	v_div_scale_f32 v6, vcc, 1.0, v2, 1.0
	v_fma_f32 v7, -v3, v5, 1.0
	v_fmac_f32_e32 v5, v7, v5
	v_mul_f32_e32 v7, v6, v5
	v_fma_f32 v9, -v3, v7, v6
	v_fmac_f32_e32 v7, v9, v5
	v_fma_f32 v3, -v3, v7, v6
	v_div_fmas_f32 v3, v3, v5, v7
	v_div_fixup_f32 v9, v3, v2, 1.0
	v_sub_f32_e32 v22, 1.0, v9
	s_and_saveexec_b64 s[6:7], s[4:5]
	s_cbranch_execz .LBB0_704
	v_add_co_u32_e32 v230, vcc, 0xf000000, v10
	s_mov_b32 s100, 0x3c00
	s_mov_b32 s101, 0
	v_addc_co_u32_e32 v231, vcc, 0, v11, vcc
	global_load_ushort v200, v[230:231], off offset:1024
	global_load_ushort v201, v[230:231], off
	v_lshl_add_u64 v[232:233], v[230:231], 0, s[100:101]
	global_load_ushort v202, v[232:233], off offset:1024
	global_load_ushort v203, v[232:233], off
	v_lshl_add_u64 v[234:235], v[232:233], 0, s[100:101]
	global_load_ushort v204, v[234:235], off offset:1024
	global_load_ushort v205, v[234:235], off
	v_lshl_add_u64 v[230:231], v[234:235], 0, s[100:101]
	global_load_ushort v206, v[230:231], off offset:1024
	global_load_ushort v207, v[230:231], off
	v_add_co_u32_e32 v2, vcc, 0xf000000, v10
	s_nop 1
	v_addc_co_u32_e32 v3, vcc, 0, v11, vcc
	s_waitcnt vmcnt(0)
	v_mov_b32_e32 v2, v200
	s_nop 0
	v_mov_b32_e32 v3, v201
	v_lshlrev_b32_e32 v2, 16, v2
	v_mul_f32_e32 v2, 0xbfb8aa3b, v2
	v_exp_f32_e32 v2, v2
	v_lshlrev_b32_e32 v3, 16, v3
	v_add_f32_e32 v2, 1.0, v2
	v_rcp_f32_e32 v2, v2
	s_nop 0
	v_fma_f32 v2, v22, v2, v9
	ds_write2st64_b32 v19, v3, v2 offset1:16
	v_sub_f32_e32 v2, 1.0, v2
	ds_write_b32 v19, v2 offset:8192
.LBB0_704:
	s_or_b64 exec, exec, s[6:7]
	v_add_co_u32_e32 v2, vcc, 0xf000000, v10
	s_mov_b64 s[16:17], 0xf003c00
	s_nop 0
	v_addc_co_u32_e32 v3, vcc, 0, v11, vcc
	global_load_ushort v25, v[2:3], off offset:2048
	global_load_ushort v13, v[2:3], off offset:3072
	s_load_dwordx2 s[8:9], s[28:29], 0x28
	s_load_dwordx2 s[6:7], s[28:29], 0x70
	v_lshl_add_u64 v[2:3], v[10:11], 0, s[16:17]
	s_and_saveexec_b64 s[16:17], s[4:5]
	s_cbranch_execz .LBB0_706
	v_add_co_u32_e32 v4, vcc, 0xf004000, v10
	s_nop 1
	v_addc_co_u32_e32 v5, vcc, 0, v11, vcc
	v_mov_b32_e32 v4, v202
	s_nop 0
	v_mov_b32_e32 v5, v203
	v_lshlrev_b32_e32 v4, 16, v4
	v_mul_f32_e32 v4, 0xbfb8aa3b, v4
	v_exp_f32_e32 v4, v4
	v_lshlrev_b32_e32 v5, 16, v5
	v_add_f32_e32 v4, 1.0, v4
	v_rcp_f32_e32 v4, v4
	s_nop 0
	v_fma_f32 v4, v22, v4, v9
	ds_write2st64_b32 v19, v5, v4 offset0:2 offset1:18
	v_sub_f32_e32 v4, 1.0, v4
	ds_write_b32 v19, v4 offset:8704
.LBB0_706:
	s_or_b64 exec, exec, s[16:17]
	v_add_co_u32_e32 v4, vcc, 0xf004000, v10
	s_nop 1
	v_addc_co_u32_e32 v5, vcc, 0, v11, vcc
	global_load_ushort v23, v[4:5], off offset:1024
	global_load_ushort v16, v[4:5], off offset:2048
	v_lshl_add_u64 v[4:5], v[10:11], 0, s[56:57]
	s_and_saveexec_b64 s[16:17], s[4:5]
	s_cbranch_execz .LBB0_708
	v_add_co_u32_e32 v6, vcc, 0xf007000, v10
	s_nop 1
	v_addc_co_u32_e32 v7, vcc, 0, v11, vcc
	v_mov_b32_e32 v6, v204
	s_nop 0
	v_mov_b32_e32 v7, v205
	v_lshlrev_b32_e32 v6, 16, v6
	v_mul_f32_e32 v6, 0xbfb8aa3b, v6
	v_exp_f32_e32 v6, v6
	v_lshlrev_b32_e32 v7, 16, v7
	v_add_f32_e32 v6, 1.0, v6
	v_rcp_f32_e32 v6, v6
	s_nop 0
	v_fma_f32 v6, v22, v6, v9
	ds_write2st64_b32 v19, v7, v6 offset0:4 offset1:20
	v_sub_f32_e32 v6, 1.0, v6
	ds_write_b32 v19, v6 offset:9216
.LBB0_708:
	s_or_b64 exec, exec, s[16:17]
	v_add_co_u32_e32 v6, vcc, 0xf008000, v10
	s_nop 1
	v_addc_co_u32_e32 v7, vcc, 0, v11, vcc
	global_load_ushort v24, v[6:7], off
	global_load_ushort v18, v[6:7], off offset:1024
	v_lshl_add_u64 v[6:7], v[10:11], 0, s[58:59]
	s_and_saveexec_b64 s[16:17], s[4:5]
	s_cbranch_execz .LBB0_710
	v_add_co_u32_e32 v26, vcc, 0xf00b000, v10
	s_nop 1
	v_addc_co_u32_e32 v27, vcc, 0, v11, vcc
	v_mov_b32_e32 v26, v206
	s_nop 0
	v_mov_b32_e32 v27, v207
	v_lshlrev_b32_e32 v26, 16, v26
	v_mul_f32_e32 v26, 0xbfb8aa3b, v26
	v_exp_f32_e32 v26, v26
	v_lshlrev_b32_e32 v27, 16, v27
	v_add_f32_e32 v26, 1.0, v26
	v_rcp_f32_e32 v26, v26
	s_nop 0
	v_fmac_f32_e32 v9, v22, v26
	ds_write2st64_b32 v19, v27, v9 offset0:6 offset1:22
	v_sub_f32_e32 v9, 1.0, v9
	ds_write_b32 v19, v9 offset:9728
